# v48 + odd-rank workgroups delay their prep items by s_sleep 40 so that the HBM bursts of the two halves interleave
# baseline (speedup 1.0000x reference)
.LBB0_898:
	s_and_b64 vcc, exec, s[40:41]
	s_cbranch_vccz .LBB0_953
	v_ashrrev_i32_e64 v177, 3, s70
	v_cmp_gt_i32_e32 vcc, 64, v177
	s_and_saveexec_b64 s[48:49], vcc
	s_cbranch_execz .LBB0_952
	s_bitcmp1_b32 s70, 3
	s_cbranch_scc0 .Lprep_nostag
	s_sleep 40
.Lprep_nostag:
	s_ashr_i32 s52, s71, 6
	v_lshlrev_b32_e64 v0, 6, s70
	v_and_b32_e32 v111, 0x1c0, v0
	s_add_u32 s54, s2, 0xf000000
	v_lshlrev_b32_e32 v0, 1, v130
	s_addc_u32 s55, s3, 0
	s_and_b32 s56, s71, 0xffffffc0
	v_and_b32_e32 v1, 24, v0
	s_waitcnt vmcnt(6)
	v_and_b32_e32 v6, 3, v130
	v_lshrrev_b32_e32 v0, 1, v130
	v_and_b32_e32 v0, 24, v0
	v_readlane_b32 s6, v255, 29
	v_or3_b32 v6, v6, v1, s56
	v_lshlrev_b32_e32 v48, 1, v0
	v_readlane_b32 s7, v255, 30
	s_waitcnt vmcnt(5)
	v_or_b32_e32 v10, 4, v6
	s_waitcnt vmcnt(4)
	v_or_b32_e32 v14, 32, v6
	s_waitcnt vmcnt(3)
	v_or_b32_e32 v18, 36, v6
	v_lshl_add_u64 v[2:3], s[6:7], 0, v[48:49]
	s_mov_b64 s[6:7], 0x2880000
	v_ashrrev_i32_e32 v7, 31, v6
	v_ashrrev_i32_e32 v11, 31, v10
	v_ashrrev_i32_e32 v15, 31, v14
	v_ashrrev_i32_e32 v19, 31, v18
	v_lshl_add_u64 v[4:5], v[2:3], 0, s[6:7]
	v_lshlrev_b64 v[8:9], 7, v[6:7]
	v_lshlrev_b64 v[12:13], 7, v[10:11]
	v_lshlrev_b64 v[16:17], 7, v[14:15]
	s_waitcnt vmcnt(2)
	v_lshlrev_b64 v[20:21], 7, v[18:19]
	s_mov_b64 s[6:7], 0x2890000
	v_lshl_add_u64 v[94:95], v[4:5], 0, v[8:9]
	v_lshl_add_u64 v[96:97], v[4:5], 0, v[12:13]
	v_lshl_add_u64 v[98:99], v[4:5], 0, v[16:17]
	v_lshl_add_u64 v[100:101], v[4:5], 0, v[20:21]
	v_lshl_add_u64 v[4:5], v[2:3], 0, s[6:7]
	v_ashrrev_i32_e32 v220, 4, v130
	s_movk_i32 s6, 0x210
	v_mul_lo_u32 v1, v220, s6
	s_lshl_b32 s6, s52, 8
	v_and_b32_e32 v218, 15, v130
	s_add_i32 s6, s6, 0
	v_lshl_add_u64 v[102:103], v[4:5], 0, v[8:9]
	v_lshl_add_u64 v[104:105], v[4:5], 0, v[12:13]
	v_lshl_add_u64 v[106:107], v[4:5], 0, v[16:17]
	v_lshl_add_u64 v[108:109], v[4:5], 0, v[20:21]
	v_lshlrev_b32_e32 v4, 5, v218
	v_lshl_add_u32 v222, v0, 2, s6
	s_mov_b64 s[6:7], 0x28a0000
	v_add3_u32 v221, 0, v1, v4
	v_lshl_add_u64 v[2:3], v[2:3], 0, s[6:7]
	v_lshlrev_b64 v[4:5], 8, v[6:7]
	v_readlane_b32 s8, v255, 37
	s_ashr_i32 s53, s52, 31
	v_lshl_add_u64 v[112:113], v[2:3], 0, v[4:5]
	v_lshlrev_b64 v[4:5], 8, v[10:11]
	s_lshl_b32 s50, s8, 9
	s_ashr_i32 s57, s56, 31
	s_lshl_b64 s[6:7], s[52:53], 2
	v_lshl_add_u64 v[114:115], v[2:3], 0, v[4:5]
	v_lshlrev_b64 v[4:5], 8, v[14:15]
	s_add_u32 s6, s2, s6
	v_lshl_add_u64 v[116:117], v[2:3], 0, v[4:5]
	v_lshlrev_b64 v[4:5], 8, v[18:19]
	s_addc_u32 s7, s3, s7
	v_lshl_add_u64 v[118:119], v[2:3], 0, v[4:5]
	v_and_b32_e64 v2, s70, 7
	v_lshlrev_b32_e32 v3, 5, v177
	v_and_b32_e32 v217, 63, v130
	s_mul_i32 s24, s8, 0x700
	v_ashrrev_i32_e32 v131, 31, v130
	v_add_u32_e32 v1, 0, v48
	s_add_u32 s58, s6, 0x300000
	v_mul_u32_u24_e32 v8, 0x210, v218
	v_or_b32_e32 v120, s56, v0
	v_lshl_add_u32 v216, v2, 11, v3
	s_mov_b32 s51, s25
	v_lshl_add_u32 v219, v130, 2, 0
	v_lshlrev_b32_e32 v110, 4, v218
	v_cmp_lt_u32_e64 s[40:41], 3, v218
	v_cmp_lt_u32_e64 s[42:43], 7, v218
	v_cmp_gt_u32_e64 s[44:45], 16, v217
	s_addc_u32 s59, s7, 0
	v_ashrrev_i32_e32 v121, 31, v120
	v_lshl_add_u32 v223, v120, 2, 0
	v_mov_b32_e32 v123, s57
	v_mov_b32_e32 v122, v120
	s_mov_b32 s53, 0
	s_mov_b64 s[60:61], 0
	s_lshl_b64 s[62:63], s[24:25], 2
	v_lshlrev_b64 v[124:125], 2, v[130:131]
	v_lshlrev_b32_e32 v48, 1, v0
	v_add_u32_e32 v224, v1, v8
	v_mov_b32_e32 v225, v216
	v_mov_b32_e32 v226, v177
	s_branch .LBB0_902
